# P1: permuted weight rows + whole-line fp16 epilogue stores (8 rows x 128 B per store)
# baseline (speedup 1.0000x reference)
; #define LAS __attribute__((address_space(3)))
; __device__ __forceinline__ void tr_tile(const float* W, int K, int N, int kt, int nt, LAS float* tile, const float* kscale, h16* dst, int mode, h16* dstG) {
;     const int tid = threadIdx.x, k0 = kt * 64, n0 = nt * 64;
;     {
;         const int kr = tid >> 4, nc = (tid & 15) * 4;
; #pragma unroll
;         for (int i = 0; i < 2; ++i) {
;             const int k = kr + 32 * i;
;             f32x4 v = {0.f, 0.f, 0.f, 0.f};
;             if (n0 + nc < N) v = *(const f32x4*)(W + (size_t)(k0 + k) * N + n0 + nc);
;             const float s = kscale ? kscale[k0 + k] : 1.f;
;             tile[k * 65 + nc] = v[0] * s; tile[k * 65 + nc + 1] = v[1] * s; tile[k * 65 + nc + 2] = v[2] * s; tile[k * 65 + nc + 3] = v[3] * s;
;         }
;     }
;     __syncthreads();
;     {
;         const int n = tid >> 3, kc = (tid & 7) * 8, gn = n0 + n;
;         if (gn < N) {
;             h16x8 o;
; #pragma unroll
;             for (int j = 0; j < 8; ++j) o[j] = (h16)tile[(kc + j) * 65 + n];
;             h16* d;
;             if (mode == 0) d = dst + (size_t)gn * K;
;             else d = (gn < 2048) ? dst + (size_t)gn * K : (gn < 2064 ? dstG + (size_t)(gn - 2048) * K : dst + (size_t)(gn - 16) * K);
;             *(h16x8*)(d + k0 + kc) = o;
.LBB0_22:
	s_or_b64 exec, exec, s[30:31]
	v_and_b32_e32 v44, 0xe0, v2
	v_lshrrev_b32_e32 v45, 1, v44
	v_lshlrev_b32_e32 v44, 2, v44
	v_and_b32_e32 v44, 0x80, v44
	v_and_b32_e32 v45, 0x60, v45
	v_or_b32_e32 v45, v45, v44
	v_and_b32_e32 v2, 0xffffff1f, v2
	v_or_b32_e32 v2, v2, v45
	v_lshlrev_b64 v[2:3], 11, v[2:3]
	v_lshl_add_u64 v[2:3], v[30:31], 0, v[2:3]
	s_ashr_i32 s11, s10, 31
	v_lshl_add_u64 v[2:3], s[10:11], 1, v[2:3]
	s_waitcnt lgkmcnt(0)
	v_cvt_pk_f16_f32 v43, v28, v29
	v_cvt_pk_f16_f32 v42, v8, v9
	v_cvt_pk_f16_f32 v41, v6, v7
	v_cvt_pk_f16_f32 v40, v4, v5
	v_lshl_add_u64 v[2:3], v[2:3], 0, v[10:11]
	global_store_dwordx4 v[2:3], v[40:43], off

; #define PG8_STAGE(bufoff, gbase, voff) do { _Pragma("unroll") for (int _i = 0; _i < 2; ++_i) \
;         __builtin_amdgcn_global_load_lds((const unsigned*)((const char*)(gbase) + (voff)[_i]), (LAS unsigned*)(lds + (bufoff) + ldsw + _i * 8192), 16, 0, 0); } while (0)
; #define PG8_LDA(dst, b, h) do { _Pragma("unroll") for (int m = 0; m < 4; ++m) _Pragma("unroll") for (int k = 0; k < 2; ++k) dst[m][k] = *(const LAS h16x8*)(lds + PG8_SA(b, h) + aoff + m * 2048 + k * 1024); } while (0)
; #define PG8_LDB(dst, b, h) do { _Pragma("unroll") for (int n = 0; n < 2; ++n) _Pragma("unroll") for (int k = 0; k < 2; ++k) dst[n][k] = *(const LAS h16x8*)(lds + PG8_SB(b, h) + boff + n * 2048 + k * 1024); } while (0)
; #define PG8_MMA(ai, bj, At, Bt) do { __builtin_amdgcn_s_setprio(1); _Pragma("unroll") for (int m = 0; m < 4; ++m) _Pragma("unroll") for (int n = 0; n < 2; ++n) _Pragma("unroll") for (int k = 0; k < 2; ++k) \
;         acc[ai][bj][m][n] = __builtin_amdgcn_mfma_f32_16x16x32_f16(Bt[n][k], At[m][k], acc[ai][bj][m][n], 0, 0, 0); __builtin_amdgcn_s_setprio(0); } while (0)
; #define PG8_WAIT_V(n) asm volatile("s_waitcnt vmcnt(" #n ")" ::: "memory")
; #define PG8_WAIT_L(n) asm volatile("s_waitcnt lgkmcnt(" #n ")" ::: "memory")
; #define PG8_BAR __builtin_amdgcn_s_barrier()
; #define PG8_SCHED __builtin_amdgcn_sched_barrier(0)
; template <class Epi>
; __device__ __forceinline__ void gemm_phase(LAS unsigned char* lds, const Gemm g, const StaticOrder& S, const Epi& E) {
;     ...
;             PG8_LDB(B0, 0, 0); PG8_SCHED; PG8_LDA(At, 0, 0); PG8_STAGE(PG8_SA(1, 1), a1 + hstep, voffA);
;             PG8_WAIT_L(8); PG8_BAR; PG8_WAIT_L(0); PG8_MMA(0, 0, At, B0); PG8_BAR; PG8_SCHED;
;             PG8_LDB(B1, 0, 1); PG8_STAGE(PG8_SB(0, 0), b2, voffB);
;             PG8_BAR; PG8_WAIT_L(0); PG8_MMA(0, 1, At, B1); PG8_BAR;
;             PG8_LDA(At, 0, 1); PG8_STAGE(PG8_SA(0, 0), a2, voffA);
;             PG8_BAR; PG8_WAIT_L(0); PG8_MMA(1, 0, At, B0); PG8_BAR; PG8_SCHED;
;             PG8_STAGE(PG8_SB(0, 1), b2 + hstep, voffB);
;             PG8_WAIT_V(6); PG8_BAR; PG8_MMA(1, 1, At, B1); PG8_BAR;
.LBB0_84:
	ds_read_b128 v[162:165], v158
	ds_read_b128 v[166:169], v158 offset:1024
	ds_read_b128 v[170:173], v158 offset:2048
	ds_read_b128 v[174:177], v158 offset:3072
	s_add_u32 s38, s34, 0xfffc0080
	s_addc_u32 s39, s35, -1
	s_cmp_eq_u32 s96, 12
	s_cselect_b32 s43, s27, s39
	s_cselect_b32 s42, s88, s38
	s_cselect_b32 s39, s25, s95
	s_cselect_b32 s38, s92, s94
	v_lshl_add_u64 v[210:211], s[34:35], 0, v[150:151]
	s_add_i32 m0, s11, 0xc000
	ds_read_b128 v[178:181], v159
	ds_read_b128 v[182:185], v159 offset:1024
	ds_read_b128 v[186:189], v159 offset:2048
	ds_read_b128 v[190:193], v159 offset:3072
	ds_read_b128 v[194:197], v159 offset:4096
	ds_read_b128 v[198:201], v159 offset:5120
	ds_read_b128 v[202:205], v159 offset:6144
	ds_read_b128 v[206:209], v159 offset:7168
	global_load_lds_dwordx4 v[210:211], off
	v_lshl_add_u64 v[210:211], s[34:35], 0, v[152:153]
	s_add_i32 m0, s11, 0xe000
	s_nop 0
	global_load_lds_dwordx4 v[210:211], off
	s_waitcnt lgkmcnt(8)
	s_barrier
	s_waitcnt lgkmcnt(0)
	s_setprio 1
	s_waitcnt lgkmcnt(0)
	v_mfma_f32_16x16x32_f16 v[124:127], v[162:165], v[178:181], v[124:127]
	v_mfma_f32_16x16x32_f16 v[120:123], v[170:173], v[178:181], v[120:123]
	v_mfma_f32_16x16x32_f16 v[116:119], v[162:165], v[186:189], v[116:119]
	v_mfma_f32_16x16x32_f16 v[112:115], v[170:173], v[186:189], v[112:115]
	v_mfma_f32_16x16x32_f16 v[100:103], v[162:165], v[194:197], v[100:103]
	v_mfma_f32_16x16x32_f16 v[96:99], v[170:173], v[194:197], v[96:99]
	v_mfma_f32_16x16x32_f16 v[84:87], v[162:165], v[202:205], v[84:87]
	v_mfma_f32_16x16x32_f16 v[80:83], v[170:173], v[202:205], v[80:83]
	v_mfma_f32_16x16x32_f16 v[124:127], v[166:169], v[182:185], v[124:127]
	v_mfma_f32_16x16x32_f16 v[120:123], v[174:177], v[182:185], v[120:123]
	v_mfma_f32_16x16x32_f16 v[116:119], v[166:169], v[190:193], v[116:119]
	v_mfma_f32_16x16x32_f16 v[112:115], v[174:177], v[190:193], v[112:115]
	v_mfma_f32_16x16x32_f16 v[100:103], v[166:169], v[198:201], v[100:103]
	v_mfma_f32_16x16x32_f16 v[96:99], v[174:177], v[198:201], v[96:99]
	v_mfma_f32_16x16x32_f16 v[84:87], v[166:169], v[206:209], v[84:87]
	v_mfma_f32_16x16x32_f16 v[80:83], v[174:177], v[206:209], v[80:83]
	s_setprio 0
	s_barrier
	s_add_i32 s80, s60, s45
	v_lshl_add_u64 v[222:223], s[38:39], 0, v[128:129]
	s_mov_b32 m0, s80
	ds_read_b128 v[210:213], v160
	ds_read_b128 v[214:217], v160 offset:1024
	ds_read_b128 v[218:221], v160 offset:2048
	ds_read_b128 v[228:231], v160 offset:3072
	global_load_lds_dwordx4 v[222:223], off
	v_lshl_add_u64 v[232:233], s[38:39], 0, v[138:139]
	s_add_i32 m0, s80, 0x2000
	s_nop 0
	global_load_lds_dwordx4 v[232:233], off
	s_barrier
	s_waitcnt lgkmcnt(0)
	s_setprio 1
	s_waitcnt lgkmcnt(0)
	v_mfma_f32_16x16x32_f16 v[108:111], v[210:213], v[178:181], v[108:111]
	v_mfma_f32_16x16x32_f16 v[104:107], v[218:221], v[178:181], v[104:107]
	v_mfma_f32_16x16x32_f16 v[92:95], v[210:213], v[186:189], v[92:95]
	v_mfma_f32_16x16x32_f16 v[88:91], v[218:221], v[186:189], v[88:91]
	v_mfma_f32_16x16x32_f16 v[76:79], v[210:213], v[194:197], v[76:79]
	v_mfma_f32_16x16x32_f16 v[72:75], v[218:221], v[194:197], v[72:75]
	v_mfma_f32_16x16x32_f16 v[68:71], v[210:213], v[202:205], v[68:71]
	v_mfma_f32_16x16x32_f16 v[64:67], v[218:221], v[202:205], v[64:67]
	v_mfma_f32_16x16x32_f16 v[108:111], v[214:217], v[182:185], v[108:111]
	v_mfma_f32_16x16x32_f16 v[104:107], v[228:231], v[182:185], v[104:107]
	v_mfma_f32_16x16x32_f16 v[92:95], v[214:217], v[190:193], v[92:95]
	v_mfma_f32_16x16x32_f16 v[88:91], v[228:231], v[190:193], v[88:91]
	v_mfma_f32_16x16x32_f16 v[76:79], v[214:217], v[198:201], v[76:79]
	v_mfma_f32_16x16x32_f16 v[72:75], v[228:231], v[198:201], v[72:75]
	v_mfma_f32_16x16x32_f16 v[68:71], v[214:217], v[206:209], v[68:71]
	v_mfma_f32_16x16x32_f16 v[64:67], v[228:231], v[206:209], v[64:67]
	s_setprio 0
	s_mov_b32 m0, s11
	v_lshl_add_u64 v[234:235], s[42:43], 0, v[144:145]
	s_barrier
	ds_read_b128 v[178:181], v159 offset:16384
	ds_read_b128 v[182:185], v159 offset:17408
	ds_read_b128 v[186:189], v159 offset:18432
	ds_read_b128 v[190:193], v159 offset:19456
	ds_read_b128 v[194:197], v159 offset:20480
	ds_read_b128 v[198:201], v159 offset:21504
	ds_read_b128 v[202:205], v159 offset:22528
	ds_read_b128 v[206:209], v159 offset:23552
	global_load_lds_dwordx4 v[234:235], off
	v_lshl_add_u64 v[236:237], s[42:43], 0, v[140:141]
	s_mov_b32 m0, s53
	s_nop 0
	global_load_lds_dwordx4 v[236:237], off
	s_barrier
	s_waitcnt lgkmcnt(0)
	s_setprio 1
	s_waitcnt lgkmcnt(0)
	v_mfma_f32_16x16x32_f16 v[60:63], v[162:165], v[178:181], v[60:63]
	v_mfma_f32_16x16x32_f16 v[56:59], v[170:173], v[178:181], v[56:59]
	v_mfma_f32_16x16x32_f16 v[52:55], v[162:165], v[186:189], v[52:55]
	v_mfma_f32_16x16x32_f16 v[48:51], v[170:173], v[186:189], v[48:51]
	v_mfma_f32_16x16x32_f16 v[36:39], v[162:165], v[194:197], v[36:39]
	v_mfma_f32_16x16x32_f16 v[32:35], v[170:173], v[194:197], v[32:35]
	v_mfma_f32_16x16x32_f16 v[20:23], v[162:165], v[202:205], v[20:23]
	v_mfma_f32_16x16x32_f16 v[16:19], v[170:173], v[202:205], v[16:19]
	v_mfma_f32_16x16x32_f16 v[60:63], v[166:169], v[182:185], v[60:63]
	v_mfma_f32_16x16x32_f16 v[56:59], v[174:177], v[182:185], v[56:59]
	v_mfma_f32_16x16x32_f16 v[52:55], v[166:169], v[190:193], v[52:55]
	v_mfma_f32_16x16x32_f16 v[48:51], v[174:177], v[190:193], v[48:51]
	v_mfma_f32_16x16x32_f16 v[36:39], v[166:169], v[198:201], v[36:39]
	v_mfma_f32_16x16x32_f16 v[32:35], v[174:177], v[198:201], v[32:35]
	v_mfma_f32_16x16x32_f16 v[20:23], v[166:169], v[206:209], v[20:23]
	v_mfma_f32_16x16x32_f16 v[16:19], v[174:177], v[206:209], v[16:19]
	s_setprio 0
	s_barrier
; #define PG8_STAGE(bufoff, gbase, voff) do { _Pragma("unroll") for (int _i = 0; _i < 2; ++_i) \
;         __builtin_amdgcn_global_load_lds((const unsigned*)((const char*)(gbase) + (voff)[_i]), (LAS unsigned*)(lds + (bufoff) + ldsw + _i * 8192), 16, 0, 0); } while (0)
; #define PG8_LDA(dst, b, h) do { _Pragma("unroll") for (int m = 0; m < 4; ++m) _Pragma("unroll") for (int k = 0; k < 2; ++k) dst[m][k] = *(const LAS h16x8*)(lds + PG8_SA(b, h) + aoff + m * 2048 + k * 1024); } while (0)
; #define PG8_LDB(dst, b, h) do { _Pragma("unroll") for (int n = 0; n < 2; ++n) _Pragma("unroll") for (int k = 0; k < 2; ++k) dst[n][k] = *(const LAS h16x8*)(lds + PG8_SB(b, h) + boff + n * 2048 + k * 1024); } while (0)
; #define PG8_MMA(ai, bj, At, Bt) do { __builtin_amdgcn_s_setprio(1); _Pragma("unroll") for (int m = 0; m < 4; ++m) _Pragma("unroll") for (int n = 0; n < 2; ++n) _Pragma("unroll") for (int k = 0; k < 2; ++k) \
;         acc[ai][bj][m][n] = __builtin_amdgcn_mfma_f32_16x16x32_f16(Bt[n][k], At[m][k], acc[ai][bj][m][n], 0, 0, 0); __builtin_amdgcn_s_setprio(0); } while (0)
; #define PG8_WAIT_V(n) asm volatile("s_waitcnt vmcnt(" #n ")" ::: "memory")
; #define PG8_WAIT_L(n) asm volatile("s_waitcnt lgkmcnt(" #n ")" ::: "memory")
; #define PG8_BAR __builtin_amdgcn_s_barrier()
; #define PG8_SCHED __builtin_amdgcn_sched_barrier(0)
; template <class Epi>
; __device__ __forceinline__ void gemm_phase(LAS unsigned char* lds, const Gemm g, const StaticOrder& S, const Epi& E) {
;     ...
;             PG8_WAIT_V(6); PG8_BAR; PG8_MMA(1, 1, At, B1); PG8_BAR;
;             PG8_LDB(B0, 1, 0); PG8_SCHED; PG8_LDA(At, 1, 0); PG8_STAGE(PG8_SA(0, 1), a2 + hstep, voffA);
;             PG8_WAIT_L(8); PG8_BAR; PG8_WAIT_L(0); PG8_MMA(0, 0, At, B0); PG8_BAR; PG8_SCHED;
;             PG8_LDB(B1, 1, 1); PG8_STAGE(PG8_SB(1, 0), b3, voffB);
;             PG8_BAR; PG8_WAIT_L(0); PG8_MMA(0, 1, At, B1); PG8_BAR;
;             PG8_LDA(At, 1, 1); PG8_STAGE(PG8_SA(1, 0), a3, voffA);
;             PG8_BAR; PG8_WAIT_L(0); PG8_MMA(1, 0, At, B0); PG8_BAR; PG8_SCHED;
	s_add_u32 vcc_lo, s38, 0x40000
	s_addc_u32 vcc_hi, s39, 0
	s_add_i32 s80, s61, s45
	v_lshl_add_u64 v[162:163], vcc, 0, v[128:129]
	s_mov_b32 m0, s80
	s_nop 0
	global_load_lds_dwordx4 v[162:163], off
	v_lshl_add_u64 v[162:163], vcc, 0, v[138:139]
	s_add_i32 m0, s80, 0x2000
	s_nop 0
	global_load_lds_dwordx4 v[162:163], off
	s_waitcnt vmcnt(6)
	s_barrier
	s_setprio 1
	v_mfma_f32_16x16x32_f16 v[44:47], v[210:213], v[178:181], v[44:47]
	v_mfma_f32_16x16x32_f16 v[40:43], v[218:221], v[178:181], v[40:43]
	v_mfma_f32_16x16x32_f16 v[28:31], v[210:213], v[186:189], v[28:31]
	v_mfma_f32_16x16x32_f16 v[24:27], v[218:221], v[186:189], v[24:27]
	v_mfma_f32_16x16x32_f16 v[12:15], v[210:213], v[194:197], v[12:15]
	v_mfma_f32_16x16x32_f16 v[8:11], v[218:221], v[194:197], v[8:11]
	v_mfma_f32_16x16x32_f16 v[4:7], v[210:213], v[202:205], v[4:7]
	v_mfma_f32_16x16x32_f16 v[0:3], v[218:221], v[202:205], v[0:3]
	v_mfma_f32_16x16x32_f16 v[44:47], v[214:217], v[182:185], v[44:47]
	v_mfma_f32_16x16x32_f16 v[40:43], v[228:231], v[182:185], v[40:43]
	v_mfma_f32_16x16x32_f16 v[28:31], v[214:217], v[190:193], v[28:31]
	v_mfma_f32_16x16x32_f16 v[24:27], v[228:231], v[190:193], v[24:27]
	v_mfma_f32_16x16x32_f16 v[12:15], v[214:217], v[198:201], v[12:15]
	v_mfma_f32_16x16x32_f16 v[8:11], v[228:231], v[198:201], v[8:11]
	v_mfma_f32_16x16x32_f16 v[4:7], v[214:217], v[206:209], v[4:7]
	v_mfma_f32_16x16x32_f16 v[0:3], v[228:231], v[206:209], v[0:3]
	s_setprio 0
	s_add_i32 s80, 0, 0x18000
	v_add_u32_e32 v161, s80, v137
	s_barrier
	ds_read_b128 v[162:165], v161
	ds_read_b128 v[166:169], v161 offset:1024
	ds_read_b128 v[170:173], v161 offset:2048
	ds_read_b128 v[174:177], v161 offset:3072
	s_add_u32 s42, s42, 0x40000
	s_addc_u32 s43, s43, 0
	s_mov_b32 m0, s54
	v_lshl_add_u64 v[210:211], s[42:43], 0, v[144:145]
	ds_read_b128 v[178:181], v159 offset:32768
	ds_read_b128 v[182:185], v159 offset:33792
	ds_read_b128 v[186:189], v159 offset:34816
	ds_read_b128 v[190:193], v159 offset:35840
	ds_read_b128 v[194:197], v159 offset:36864
	ds_read_b128 v[198:201], v159 offset:37888
	ds_read_b128 v[202:205], v159 offset:38912
	ds_read_b128 v[206:209], v159 offset:39936
	global_load_lds_dwordx4 v[210:211], off
	v_lshl_add_u64 v[210:211], s[42:43], 0, v[140:141]
	s_mov_b32 m0, s55
	s_nop 0
	global_load_lds_dwordx4 v[210:211], off
	s_waitcnt lgkmcnt(8)
	s_barrier
	s_waitcnt lgkmcnt(0)
	s_setprio 1
	s_waitcnt lgkmcnt(0)
	v_mfma_f32_16x16x32_f16 v[124:127], v[162:165], v[178:181], v[124:127]
	v_mfma_f32_16x16x32_f16 v[120:123], v[170:173], v[178:181], v[120:123]
	v_mfma_f32_16x16x32_f16 v[116:119], v[162:165], v[186:189], v[116:119]
	v_mfma_f32_16x16x32_f16 v[112:115], v[170:173], v[186:189], v[112:115]
	v_mfma_f32_16x16x32_f16 v[100:103], v[162:165], v[194:197], v[100:103]
	v_mfma_f32_16x16x32_f16 v[96:99], v[170:173], v[194:197], v[96:99]
	v_mfma_f32_16x16x32_f16 v[84:87], v[162:165], v[202:205], v[84:87]
	v_mfma_f32_16x16x32_f16 v[80:83], v[170:173], v[202:205], v[80:83]
	v_mfma_f32_16x16x32_f16 v[124:127], v[166:169], v[182:185], v[124:127]
	v_mfma_f32_16x16x32_f16 v[120:123], v[174:177], v[182:185], v[120:123]
	v_mfma_f32_16x16x32_f16 v[116:119], v[166:169], v[190:193], v[116:119]
	v_mfma_f32_16x16x32_f16 v[112:115], v[174:177], v[190:193], v[112:115]
	v_mfma_f32_16x16x32_f16 v[100:103], v[166:169], v[198:201], v[100:103]
	v_mfma_f32_16x16x32_f16 v[96:99], v[174:177], v[198:201], v[96:99]
	v_mfma_f32_16x16x32_f16 v[84:87], v[166:169], v[206:209], v[84:87]
	v_mfma_f32_16x16x32_f16 v[80:83], v[174:177], v[206:209], v[80:83]
	s_setprio 0
	s_barrier
	s_add_i32 s42, 0, 0x1c000
	s_add_i32 s43, s80, s45
	v_add_u32_e32 v161, s42, v137
	v_lshl_add_u64 v[222:223], v[222:223], 0, s[0:1]
	s_mov_b32 m0, s43
	ds_read_b128 v[210:213], v161
	ds_read_b128 v[214:217], v161 offset:1024
	ds_read_b128 v[218:221], v161 offset:2048
	ds_read_b128 v[228:231], v161 offset:3072
	global_load_lds_dwordx4 v[222:223], off
	v_lshl_add_u64 v[222:223], v[232:233], 0, s[0:1]
	s_add_i32 m0, s43, 0x2000
	s_nop 0
	global_load_lds_dwordx4 v[222:223], off
	s_barrier
	s_waitcnt lgkmcnt(0)
	s_setprio 1
	s_waitcnt lgkmcnt(0)
	v_mfma_f32_16x16x32_f16 v[108:111], v[210:213], v[178:181], v[108:111]
	v_mfma_f32_16x16x32_f16 v[104:107], v[218:221], v[178:181], v[104:107]
	v_mfma_f32_16x16x32_f16 v[92:95], v[210:213], v[186:189], v[92:95]
	v_mfma_f32_16x16x32_f16 v[88:91], v[218:221], v[186:189], v[88:91]
	v_mfma_f32_16x16x32_f16 v[76:79], v[210:213], v[194:197], v[76:79]
	v_mfma_f32_16x16x32_f16 v[72:75], v[218:221], v[194:197], v[72:75]
	v_mfma_f32_16x16x32_f16 v[68:71], v[210:213], v[202:205], v[68:71]
	v_mfma_f32_16x16x32_f16 v[64:67], v[218:221], v[202:205], v[64:67]
	v_mfma_f32_16x16x32_f16 v[108:111], v[214:217], v[182:185], v[108:111]
	v_mfma_f32_16x16x32_f16 v[104:107], v[228:231], v[182:185], v[104:107]
	v_mfma_f32_16x16x32_f16 v[92:95], v[214:217], v[190:193], v[92:95]
	v_mfma_f32_16x16x32_f16 v[88:91], v[228:231], v[190:193], v[88:91]
	v_mfma_f32_16x16x32_f16 v[76:79], v[214:217], v[198:201], v[76:79]
	v_mfma_f32_16x16x32_f16 v[72:75], v[228:231], v[198:201], v[72:75]
	v_mfma_f32_16x16x32_f16 v[68:71], v[214:217], v[206:209], v[68:71]
	v_mfma_f32_16x16x32_f16 v[64:67], v[228:231], v[206:209], v[64:67]
	s_setprio 0
	s_mov_b32 m0, s56
	v_lshl_add_u64 v[222:223], v[234:235], 0, s[0:1]
	s_barrier
	ds_read_b128 v[178:181], v159 offset:49152
	ds_read_b128 v[182:185], v159 offset:50176
	ds_read_b128 v[186:189], v159 offset:51200
	ds_read_b128 v[190:193], v159 offset:52224
	ds_read_b128 v[194:197], v159 offset:53248
	ds_read_b128 v[198:201], v159 offset:54272
	ds_read_b128 v[202:205], v159 offset:55296
	ds_read_b128 v[206:209], v159 offset:56320
	global_load_lds_dwordx4 v[222:223], off
	v_lshl_add_u64 v[222:223], v[236:237], 0, s[0:1]
	s_mov_b32 m0, s57
	s_nop 0
	global_load_lds_dwordx4 v[222:223], off
	s_barrier
; #define PG8_WAIT_V(n) asm volatile("s_waitcnt vmcnt(" #n ")" ::: "memory")
; #define PG8_WAIT_L(n) asm volatile("s_waitcnt lgkmcnt(" #n ")" ::: "memory")
; template <class Epi>
; __device__ __forceinline__ void gemm_phase(LAS unsigned char* lds, const Gemm g, const StaticOrder& S, const Epi& E) {
;     ...
;             PG8_BAR; PG8_WAIT_L(0); PG8_MMA(1, 0, At, B0); PG8_BAR; PG8_SCHED;
;             PG8_STAGE(PG8_SB(1, 1), b3 + hstep, voffB);
;             PG8_WAIT_V(6); PG8_BAR; PG8_MMA(1, 1, At, B1); PG8_BAR;
;         }
;         if constexpr (!Epi::AFTER_DRAIN) E(acc, cur, wr, wc, fr, fq);
;     __device__ __forceinline__ void operator()(const f32x4 (&acc)[2][2][4][2], const pg8::Unit& u, int wr, int wc, int fr, int fq) const {
;         const int row0 = u.pm * 256 + wr * 64 + fr, col0 = u.pn * 256 + wc * 32 + 8 * fq;
; #pragma unroll
;         for (int ai = 0; ai < 2; ++ai)
; #pragma unroll
;             for (int m = 0; m < 4; ++m) {
;                 const int row = row0 + ai * 128 + m * 16;
;                 float ss = 0.f, rstd = 1.f;
;                 if (MODE == 2) rstd = rsqrtf(rowss[row] * (1.f / 1024.f) + EPS);
; #pragma unroll
;                 for (int bj = 0; bj < 2; ++bj) {
;                     const int c = col0 + bj * 128;
;                     f32x4 v0 = acc[ai][bj][m][0], v1 = acc[ai][bj][m][1];
;                     if (MODE == 1) {
;                         const float* rp = res + (size_t)row * ldres + c;
;                         v0 += *(const f32x4*)rp; v1 += *(const f32x4*)(rp + 4);
;                     }
;                     if (MODE == 3) {
;                         const h16x8 r8 = *(const h16x8*)(res16 + (size_t)row * ldres + c);
; #pragma unroll
;                         for (int j = 0; j < 4; ++j) { v0[j] += (float)r8[j]; v1[j] += (float)r8[4 + j]; }
;                     }
;                     if (MODE == 1 || MODE == 3) {
;                         ss += v0[0] * v0[0] + v0[1] * v0[1] + v0[2] * v0[2] + v0[3] * v0[3] + v1[0] * v1[0] + v1[1] * v1[1] + v1[2] * v1[2] + v1[3] * v1[3];
;                     }
;                     if (MODE == 2) {
; #pragma unroll
;                         for (int j = 0; j < 4; ++j) { float a = fmaxf(v0[j] * rstd, 0.f), b = fmaxf(v1[j] * rstd, 0.f); v0[j] = a * a; v1[j] = b * b; }
;                     }
;                     *(h16x8*)(o16 + (size_t)row * ld16 + c) = pack8(v0, v1);
	s_waitcnt lgkmcnt(0)
	s_setprio 1
	s_waitcnt lgkmcnt(0)
	v_mfma_f32_16x16x32_f16 v[60:63], v[162:165], v[178:181], v[60:63]
	v_mfma_f32_16x16x32_f16 v[56:59], v[170:173], v[178:181], v[56:59]
	v_mfma_f32_16x16x32_f16 v[52:55], v[162:165], v[186:189], v[52:55]
	v_mfma_f32_16x16x32_f16 v[48:51], v[170:173], v[186:189], v[48:51]
	v_mfma_f32_16x16x32_f16 v[36:39], v[162:165], v[194:197], v[36:39]
	v_mfma_f32_16x16x32_f16 v[32:35], v[170:173], v[194:197], v[32:35]
	v_mfma_f32_16x16x32_f16 v[20:23], v[162:165], v[202:205], v[20:23]
	v_mfma_f32_16x16x32_f16 v[16:19], v[170:173], v[202:205], v[16:19]
	v_mfma_f32_16x16x32_f16 v[60:63], v[166:169], v[182:185], v[60:63]
	v_mfma_f32_16x16x32_f16 v[56:59], v[174:177], v[182:185], v[56:59]
	v_mfma_f32_16x16x32_f16 v[52:55], v[166:169], v[190:193], v[52:55]
	v_mfma_f32_16x16x32_f16 v[48:51], v[174:177], v[190:193], v[48:51]
	v_mfma_f32_16x16x32_f16 v[36:39], v[166:169], v[198:201], v[36:39]
	v_mfma_f32_16x16x32_f16 v[32:35], v[174:177], v[198:201], v[32:35]
	v_mfma_f32_16x16x32_f16 v[20:23], v[166:169], v[206:209], v[20:23]
	v_mfma_f32_16x16x32_f16 v[16:19], v[174:177], v[206:209], v[16:19]
	s_setprio 0
	s_barrier
	s_add_u32 s38, s38, 0x40080
	s_addc_u32 s39, s39, 0
	s_add_i32 s42, s42, s45
	v_lshl_add_u64 v[162:163], s[38:39], 0, v[128:129]
	s_mov_b32 m0, s42
	s_nop 0
	global_load_lds_dwordx4 v[162:163], off
	v_lshl_add_u64 v[162:163], s[38:39], 0, v[138:139]
	s_add_i32 m0, s42, 0x2000
	s_nop 0
	global_load_lds_dwordx4 v[162:163], off
	s_waitcnt vmcnt(6)
	s_barrier
	s_setprio 1
	v_mfma_f32_16x16x32_f16 v[44:47], v[210:213], v[178:181], v[44:47]
	v_mfma_f32_16x16x32_f16 v[40:43], v[218:221], v[178:181], v[40:43]
	v_mfma_f32_16x16x32_f16 v[28:31], v[210:213], v[186:189], v[28:31]
	v_mfma_f32_16x16x32_f16 v[24:27], v[218:221], v[186:189], v[24:27]
	v_mfma_f32_16x16x32_f16 v[12:15], v[210:213], v[194:197], v[12:15]
	v_mfma_f32_16x16x32_f16 v[8:11], v[218:221], v[194:197], v[8:11]
	v_mfma_f32_16x16x32_f16 v[4:7], v[210:213], v[202:205], v[4:7]
	v_mfma_f32_16x16x32_f16 v[0:3], v[218:221], v[202:205], v[0:3]
	v_mfma_f32_16x16x32_f16 v[44:47], v[214:217], v[182:185], v[44:47]
	v_mfma_f32_16x16x32_f16 v[40:43], v[228:231], v[182:185], v[40:43]
	v_mfma_f32_16x16x32_f16 v[28:31], v[214:217], v[190:193], v[28:31]
	v_mfma_f32_16x16x32_f16 v[24:27], v[228:231], v[190:193], v[24:27]
	v_mfma_f32_16x16x32_f16 v[12:15], v[214:217], v[198:201], v[12:15]
	v_mfma_f32_16x16x32_f16 v[8:11], v[228:231], v[198:201], v[8:11]
	v_mfma_f32_16x16x32_f16 v[4:7], v[214:217], v[206:209], v[4:7]
	v_mfma_f32_16x16x32_f16 v[0:3], v[228:231], v[206:209], v[0:3]
	s_setprio 0
	s_add_i32 s96, s96, 2
	s_add_u32 s34, s34, 0x100
	s_addc_u32 s35, s35, 0
	s_add_u32 s94, s94, 0x100
	s_addc_u32 s95, s95, 0
	s_cmp_gt_u32 s96, 13
	s_barrier
	s_cbranch_scc0 .LBB0_84
	v_lshl_add_u32 v161, s10, 8, v135
	v_lshl_or_b32 v162, s63, 8, v143
	v_and_b32_e32 v164, 0x60, v143
	v_add_lshl_u32 v162, v162, v164, 1
	v_mov_b32_e32 v163, 0
	v_mov_b64_e32 v[166:167], s[90:91]
	v_mad_i64_i32 v[164:165], s[34:35], v161, s62, v[166:167]
	v_lshl_add_u64 v[164:165], v[164:165], 0, v[162:163]
	v_and_b32_e32 v168, 8, v135
	v_cmp_eq_u32_e64 s[98:99], 0, v168
	v_mov_b32_e32 v168, 0xffff1040
	v_cndmask_b32_e64 v170, v168, 0, s[98:99]
	v_cndmask_b32_e64 v171, -1, 0, s[98:99]
	v_mov_b32_e32 v168, 0xf040
	v_cndmask_b32_e64 v172, 0, v168, s[98:99]
	v_mov_b32_e32 v173, 0
	s_mov_b32 s100, 0x1e000
	s_mov_b32 s101, 0
	v_cvt_pk_f16_f32 v124, v124, v125
	v_cvt_pk_f16_f32 v125, v126, v127
	v_cvt_pk_f16_f32 v126, v120, v121
	v_cvt_pk_f16_f32 v127, v122, v123
	v_cvt_pk_f16_f32 v108, v108, v109
	v_cvt_pk_f16_f32 v109, v110, v111
	v_cvt_pk_f16_f32 v110, v104, v105
	v_cvt_pk_f16_f32 v111, v106, v107
	s_nop 1
	v_mov_b32_dpp v176, v108 row_ror:8 row_mask:0xf bank_mask:0xf
	v_mov_b32_dpp v177, v109 row_ror:8 row_mask:0xf bank_mask:0xf
	v_mov_b32_dpp v178, v110 row_ror:8 row_mask:0xf bank_mask:0xf
	v_mov_b32_dpp v179, v111 row_ror:8 row_mask:0xf bank_mask:0xf
	v_cndmask_b32_e64 v108, v176, v124, s[98:99]
	v_cndmask_b32_e64 v109, v177, v125, s[98:99]
	v_cndmask_b32_e64 v110, v178, v126, s[98:99]
	v_cndmask_b32_e64 v111, v179, v127, s[98:99]
	v_cndmask_b32_e64 v176, v124, v176, s[98:99]
	v_cndmask_b32_e64 v177, v125, v177, s[98:99]
	v_cndmask_b32_e64 v178, v126, v178, s[98:99]
	v_cndmask_b32_e64 v179, v127, v179, s[98:99]
	v_lshl_add_u64 v[180:181], v[164:165], 0, v[170:171]
	v_lshl_add_u64 v[182:183], v[164:165], 0, v[172:173]
	global_store_dwordx4 v[180:181], v[108:111], off
	global_store_dwordx4 v[182:183], v[176:179], off
	v_lshl_add_u64 v[164:165], v[164:165], 0, s[100:101]
	v_cvt_pk_f16_f32 v116, v116, v117
	v_cvt_pk_f16_f32 v117, v118, v119
	v_cvt_pk_f16_f32 v118, v112, v113
	v_cvt_pk_f16_f32 v119, v114, v115
	v_cvt_pk_f16_f32 v92, v92, v93
	v_cvt_pk_f16_f32 v93, v94, v95
	v_cvt_pk_f16_f32 v94, v88, v89
	v_cvt_pk_f16_f32 v95, v90, v91
	s_nop 1
	v_mov_b32_dpp v184, v92 row_ror:8 row_mask:0xf bank_mask:0xf
	v_mov_b32_dpp v185, v93 row_ror:8 row_mask:0xf bank_mask:0xf
	v_mov_b32_dpp v186, v94 row_ror:8 row_mask:0xf bank_mask:0xf
	v_mov_b32_dpp v187, v95 row_ror:8 row_mask:0xf bank_mask:0xf
	v_cndmask_b32_e64 v92, v184, v116, s[98:99]
	v_cndmask_b32_e64 v93, v185, v117, s[98:99]
	v_cndmask_b32_e64 v94, v186, v118, s[98:99]
	v_cndmask_b32_e64 v95, v187, v119, s[98:99]
	v_cndmask_b32_e64 v184, v116, v184, s[98:99]
	v_cndmask_b32_e64 v185, v117, v185, s[98:99]
	v_cndmask_b32_e64 v186, v118, v186, s[98:99]
	v_cndmask_b32_e64 v187, v119, v187, s[98:99]
	v_lshl_add_u64 v[188:189], v[164:165], 0, v[170:171]
	v_lshl_add_u64 v[190:191], v[164:165], 0, v[172:173]
	global_store_dwordx4 v[188:189], v[92:95], off
;     __device__ __forceinline__ void operator()(const f32x4 (&acc)[2][2][4][2], const pg8::Unit& u, int wr, int wc, int fr, int fq) const {
;         const int row0 = u.pm * 256 + wr * 64 + fr, col0 = u.pn * 256 + wc * 32 + 8 * fq;
; #pragma unroll
;         for (int ai = 0; ai < 2; ++ai)
; #pragma unroll
;             for (int m = 0; m < 4; ++m) {
;                 const int row = row0 + ai * 128 + m * 16;
;                 float ss = 0.f, rstd = 1.f;
;                 if (MODE == 2) rstd = rsqrtf(rowss[row] * (1.f / 1024.f) + EPS);
; #pragma unroll
;                 for (int bj = 0; bj < 2; ++bj) {
;                     const int c = col0 + bj * 128;
;                     f32x4 v0 = acc[ai][bj][m][0], v1 = acc[ai][bj][m][1];
;                     if (MODE == 1) {
;                         const float* rp = res + (size_t)row * ldres + c;
;                         v0 += *(const f32x4*)rp; v1 += *(const f32x4*)(rp + 4);
;                     }
;                     if (MODE == 3) {
;                         const h16x8 r8 = *(const h16x8*)(res16 + (size_t)row * ldres + c);
; #pragma unroll
;                         for (int j = 0; j < 4; ++j) { v0[j] += (float)r8[j]; v1[j] += (float)r8[4 + j]; }
;                     }
;                     if (MODE == 1 || MODE == 3) {
;                         ss += v0[0] * v0[0] + v0[1] * v0[1] + v0[2] * v0[2] + v0[3] * v0[3] + v1[0] * v1[0] + v1[1] * v1[1] + v1[2] * v1[2] + v1[3] * v1[3];
;                     }
;                     if (MODE == 2) {
; #pragma unroll
;                         for (int j = 0; j < 4; ++j) { float a = fmaxf(v0[j] * rstd, 0.f), b = fmaxf(v1[j] * rstd, 0.f); v0[j] = a * a; v1[j] = b * b; }
;                     }
;                     *(h16x8*)(o16 + (size_t)row * ld16 + c) = pack8(v0, v1);
	global_store_dwordx4 v[190:191], v[184:187], off
	v_lshl_add_u64 v[164:165], v[164:165], 0, s[100:101]
	v_cvt_pk_f16_f32 v100, v100, v101
	v_cvt_pk_f16_f32 v101, v102, v103
	v_cvt_pk_f16_f32 v102, v96, v97
	v_cvt_pk_f16_f32 v103, v98, v99
	v_cvt_pk_f16_f32 v76, v76, v77
	v_cvt_pk_f16_f32 v77, v78, v79
	v_cvt_pk_f16_f32 v78, v72, v73
	v_cvt_pk_f16_f32 v79, v74, v75
	s_nop 1
	v_mov_b32_dpp v176, v76 row_ror:8 row_mask:0xf bank_mask:0xf
	v_mov_b32_dpp v177, v77 row_ror:8 row_mask:0xf bank_mask:0xf
	v_mov_b32_dpp v178, v78 row_ror:8 row_mask:0xf bank_mask:0xf
	v_mov_b32_dpp v179, v79 row_ror:8 row_mask:0xf bank_mask:0xf
	v_cndmask_b32_e64 v76, v176, v100, s[98:99]
	v_cndmask_b32_e64 v77, v177, v101, s[98:99]
	v_cndmask_b32_e64 v78, v178, v102, s[98:99]
	v_cndmask_b32_e64 v79, v179, v103, s[98:99]
	v_cndmask_b32_e64 v176, v100, v176, s[98:99]
	v_cndmask_b32_e64 v177, v101, v177, s[98:99]
	v_cndmask_b32_e64 v178, v102, v178, s[98:99]
	v_cndmask_b32_e64 v179, v103, v179, s[98:99]
	v_lshl_add_u64 v[180:181], v[164:165], 0, v[170:171]
	v_lshl_add_u64 v[182:183], v[164:165], 0, v[172:173]
	global_store_dwordx4 v[180:181], v[76:79], off
	global_store_dwordx4 v[182:183], v[176:179], off
	v_lshl_add_u64 v[164:165], v[164:165], 0, s[100:101]
	v_cvt_pk_f16_f32 v84, v84, v85
	v_cvt_pk_f16_f32 v85, v86, v87
	v_cvt_pk_f16_f32 v86, v80, v81
	v_cvt_pk_f16_f32 v87, v82, v83
	v_cvt_pk_f16_f32 v68, v68, v69
	v_cvt_pk_f16_f32 v69, v70, v71
	v_cvt_pk_f16_f32 v70, v64, v65
	v_cvt_pk_f16_f32 v71, v66, v67
	s_nop 1
	v_mov_b32_dpp v184, v68 row_ror:8 row_mask:0xf bank_mask:0xf
	v_mov_b32_dpp v185, v69 row_ror:8 row_mask:0xf bank_mask:0xf
	v_mov_b32_dpp v186, v70 row_ror:8 row_mask:0xf bank_mask:0xf
	v_mov_b32_dpp v187, v71 row_ror:8 row_mask:0xf bank_mask:0xf
	v_cndmask_b32_e64 v68, v184, v84, s[98:99]
	v_cndmask_b32_e64 v69, v185, v85, s[98:99]
	v_cndmask_b32_e64 v70, v186, v86, s[98:99]
	v_cndmask_b32_e64 v71, v187, v87, s[98:99]
	v_cndmask_b32_e64 v184, v84, v184, s[98:99]
	v_cndmask_b32_e64 v185, v85, v185, s[98:99]
	v_cndmask_b32_e64 v186, v86, v186, s[98:99]
	v_cndmask_b32_e64 v187, v87, v187, s[98:99]
	v_lshl_add_u64 v[188:189], v[164:165], 0, v[170:171]
	v_lshl_add_u64 v[190:191], v[164:165], 0, v[172:173]
	global_store_dwordx4 v[188:189], v[68:71], off
	global_store_dwordx4 v[190:191], v[184:187], off
	v_add_co_u32_e32 v164, vcc, 0x96000, v164
	s_nop 1
	v_addc_co_u32_e32 v165, vcc, 0, v165, vcc
	v_cvt_pk_f16_f32 v60, v60, v61
	v_cvt_pk_f16_f32 v61, v62, v63
	v_cvt_pk_f16_f32 v62, v56, v57
	v_cvt_pk_f16_f32 v63, v58, v59
	v_cvt_pk_f16_f32 v44, v44, v45
	v_cvt_pk_f16_f32 v45, v46, v47
	v_cvt_pk_f16_f32 v46, v40, v41
	v_cvt_pk_f16_f32 v47, v42, v43
	s_nop 1
	v_mov_b32_dpp v176, v44 row_ror:8 row_mask:0xf bank_mask:0xf
	v_mov_b32_dpp v177, v45 row_ror:8 row_mask:0xf bank_mask:0xf
	v_mov_b32_dpp v178, v46 row_ror:8 row_mask:0xf bank_mask:0xf
	v_mov_b32_dpp v179, v47 row_ror:8 row_mask:0xf bank_mask:0xf
	v_cndmask_b32_e64 v44, v176, v60, s[98:99]
	v_cndmask_b32_e64 v45, v177, v61, s[98:99]
	v_cndmask_b32_e64 v46, v178, v62, s[98:99]
	v_cndmask_b32_e64 v47, v179, v63, s[98:99]
	v_cndmask_b32_e64 v176, v60, v176, s[98:99]
	v_cndmask_b32_e64 v177, v61, v177, s[98:99]
	v_cndmask_b32_e64 v178, v62, v178, s[98:99]
	v_cndmask_b32_e64 v179, v63, v179, s[98:99]
	v_lshl_add_u64 v[180:181], v[164:165], 0, v[170:171]
	v_lshl_add_u64 v[182:183], v[164:165], 0, v[172:173]
	global_store_dwordx4 v[180:181], v[44:47], off
	global_store_dwordx4 v[182:183], v[176:179], off
	v_lshl_add_u64 v[164:165], v[164:165], 0, s[100:101]
	v_cvt_pk_f16_f32 v52, v52, v53
	v_cvt_pk_f16_f32 v53, v54, v55
	v_cvt_pk_f16_f32 v54, v48, v49
	v_cvt_pk_f16_f32 v55, v50, v51
	v_cvt_pk_f16_f32 v28, v28, v29
	v_cvt_pk_f16_f32 v29, v30, v31
	v_cvt_pk_f16_f32 v30, v24, v25
	v_cvt_pk_f16_f32 v31, v26, v27
	s_nop 1
	v_mov_b32_dpp v184, v28 row_ror:8 row_mask:0xf bank_mask:0xf
	v_mov_b32_dpp v185, v29 row_ror:8 row_mask:0xf bank_mask:0xf
	v_mov_b32_dpp v186, v30 row_ror:8 row_mask:0xf bank_mask:0xf
	v_mov_b32_dpp v187, v31 row_ror:8 row_mask:0xf bank_mask:0xf
	v_cndmask_b32_e64 v28, v184, v52, s[98:99]
	v_cndmask_b32_e64 v29, v185, v53, s[98:99]
	v_cndmask_b32_e64 v30, v186, v54, s[98:99]
	v_cndmask_b32_e64 v31, v187, v55, s[98:99]
	v_cndmask_b32_e64 v184, v52, v184, s[98:99]
	v_cndmask_b32_e64 v185, v53, v185, s[98:99]
	v_cndmask_b32_e64 v186, v54, v186, s[98:99]
	v_cndmask_b32_e64 v187, v55, v187, s[98:99]
	v_lshl_add_u64 v[188:189], v[164:165], 0, v[170:171]
	v_lshl_add_u64 v[190:191], v[164:165], 0, v[172:173]
	global_store_dwordx4 v[188:189], v[28:31], off
	global_store_dwordx4 v[190:191], v[184:187], off
	v_lshl_add_u64 v[164:165], v[164:165], 0, s[100:101]
	v_cvt_pk_f16_f32 v36, v36, v37
	v_cvt_pk_f16_f32 v37, v38, v39
	v_cvt_pk_f16_f32 v38, v32, v33
	v_cvt_pk_f16_f32 v39, v34, v35
	v_cvt_pk_f16_f32 v12, v12, v13
	v_cvt_pk_f16_f32 v13, v14, v15
	v_cvt_pk_f16_f32 v14, v8, v9
	v_cvt_pk_f16_f32 v15, v10, v11
	s_nop 1
	v_mov_b32_dpp v176, v12 row_ror:8 row_mask:0xf bank_mask:0xf
	v_mov_b32_dpp v177, v13 row_ror:8 row_mask:0xf bank_mask:0xf
	v_mov_b32_dpp v178, v14 row_ror:8 row_mask:0xf bank_mask:0xf
	v_mov_b32_dpp v179, v15 row_ror:8 row_mask:0xf bank_mask:0xf
	v_cndmask_b32_e64 v12, v176, v36, s[98:99]
	v_cndmask_b32_e64 v13, v177, v37, s[98:99]
	v_cndmask_b32_e64 v14, v178, v38, s[98:99]
	v_cndmask_b32_e64 v15, v179, v39, s[98:99]
	v_cndmask_b32_e64 v176, v36, v176, s[98:99]
	v_cndmask_b32_e64 v177, v37, v177, s[98:99]
	v_cndmask_b32_e64 v178, v38, v178, s[98:99]
	v_cndmask_b32_e64 v179, v39, v179, s[98:99]
	v_lshl_add_u64 v[180:181], v[164:165], 0, v[170:171]
	v_lshl_add_u64 v[182:183], v[164:165], 0, v[172:173]
	global_store_dwordx4 v[180:181], v[12:15], off
	global_store_dwordx4 v[182:183], v[176:179], off
	v_lshl_add_u64 v[164:165], v[164:165], 0, s[100:101]
	v_cvt_pk_f16_f32 v20, v20, v21
	v_cvt_pk_f16_f32 v21, v22, v23
	v_cvt_pk_f16_f32 v22, v16, v17
	v_cvt_pk_f16_f32 v23, v18, v19
	v_cvt_pk_f16_f32 v4, v4, v5
	v_cvt_pk_f16_f32 v5, v6, v7
	v_cvt_pk_f16_f32 v6, v0, v1
	v_cvt_pk_f16_f32 v7, v2, v3
	s_nop 1
	v_mov_b32_dpp v184, v4 row_ror:8 row_mask:0xf bank_mask:0xf
	v_mov_b32_dpp v185, v5 row_ror:8 row_mask:0xf bank_mask:0xf
	v_mov_b32_dpp v186, v6 row_ror:8 row_mask:0xf bank_mask:0xf
	v_mov_b32_dpp v187, v7 row_ror:8 row_mask:0xf bank_mask:0xf
	v_cndmask_b32_e64 v4, v184, v20, s[98:99]
	v_cndmask_b32_e64 v5, v185, v21, s[98:99]
	v_cndmask_b32_e64 v6, v186, v22, s[98:99]
	v_cndmask_b32_e64 v7, v187, v23, s[98:99]
	v_cndmask_b32_e64 v184, v20, v184, s[98:99]
	v_cndmask_b32_e64 v185, v21, v185, s[98:99]
	v_cndmask_b32_e64 v186, v22, v186, s[98:99]
	v_cndmask_b32_e64 v187, v23, v187, s[98:99]
	v_lshl_add_u64 v[188:189], v[164:165], 0, v[170:171]
	v_lshl_add_u64 v[190:191], v[164:165], 0, v[172:173]
	global_store_dwordx4 v[188:189], v[4:7], off
	global_store_dwordx4 v[190:191], v[184:187], off
	s_and_b64 vcc, exec, s[8:9]
	s_mov_b32 s63, s24
	s_mov_b32 s10, s26
	s_mov_b64 s[38:39], s[30:31]
	s_mov_b64 s[34:35], s[28:29]
	s_cbranch_vccz .LBB0_81
; #define PG8_WAIT_V(n) asm volatile("s_waitcnt vmcnt(" #n ")" ::: "memory")
; #define PG8_BAR __builtin_amdgcn_s_barrier()
; template <class Epi>
; __device__ __forceinline__ void gemm_phase(LAS unsigned char* lds, const Gemm g, const StaticOrder& S, const Epi& E) {
;     ...
;     PG8_WAIT_V(0);
;     if (wr == 0) PG8_BAR;
;     PG8_BAR;
	s_waitcnt vmcnt(0)
	s_cmpk_gt_u32 s44, 0xff
	s_cbranch_scc1 .LBB0_88
	s_barrier
